# FOX attention loop software-pipelined: QK of next tile (decay as MFMA C operand) overlapped with softmax/PV of current tile
# baseline (speedup 1.0000x reference)
; #define MFMA32(a, b, c) __builtin_amdgcn_mfma_f32_32x32x16_bf16((a), (b), (c), 0, 0, 0)
;     ...
;     auto ld_tile = [&](int kt) {
;         const unsigned char* Kt = (const unsigned char*)(K + (size_t)(64 * kt) * DQK);
;         const unsigned char* Vt = (const unsigned char*)(VT + 64 * kt);
; #pragma unroll
;         for (int j = 0; j < NKL; ++j) rk[j] = *(const u32x4*)(Kt + (okk + j * 4096));
; #pragma unroll
;         for (int j = 0; j < 2; ++j) rv[j] = *(const u32x4*)(Vt + (ovv + j * svv));
;         if (cdec && tid < 16) rc = *(const f32x4*)(cdec + 64 * kt + 4 * tid);
;     };
;     auto st_tile = [&](int buf) {
;         bf16_t* sK = (bf16_t*)(smem + buf * ATT_BUF); bf16_t* sV = (bf16_t*)(smem + buf * ATT_BUF + 13312); float* sC = (float*)(smem + buf * ATT_BUF + 22528);
; #pragma unroll
;         for (int j = 0; j < NKL; ++j) { const int c = tid + 256 * j, row = c / KCH, kc = (c % KCH) * 8; *(u32x4*)(sK + row * KS + kc) = rk[j]; }
; #pragma unroll
;         for (int j = 0; j < 2; ++j) { const int c = tid + 256 * j, row = c >> 3, kc = (c & 7) * 8; *(u32x4*)(sV + row * LS + kc) = rv[j]; }
;         if (cdec && tid < 16) *(f32x4*)(sC + 4 * tid) = rc;
;     };
;     ld_tile(DESC ? ntiles - 1 : 0);
;     __syncthreads();
;     st_tile(0);
;     ...
;             for (int s = 0; s < NKS; ++s) {
;                 const bf16x8 k0 = *(const bf16x8*)(sK + r * KS + 16 * s + 8 * h), k1 = *(const bf16x8*)(sK + (32 + r) * KS + 16 * s + 8 * h);
;                 sc[0] = MFMA32(k0, qf[s], sc[0]);
;                 sc[1] = MFMA32(k1, qf[s], sc[1]);
;             }
.LBB0_739:
	s_or_b64 exec, exec, s[6:7]
	v_ashrrev_i32_e32 v11, 31, v8
	v_lshrrev_b32_e32 v11, 29, v11
	v_add_u32_e32 v11, v8, v11
	v_lshrrev_b32_e32 v12, 3, v11
	v_and_b32_e32 v11, -8, v11
	s_movk_i32 s0, 0x48
	v_sub_u32_e32 v11, v8, v11
	v_mul_lo_u32 v12, v12, s0
	v_lshlrev_b32_e32 v113, 1, v12
	v_lshlrev_b32_e32 v12, 4, v11
	v_add3_u32 v12, s33, v113, v12
	v_add_u32_e32 v13, 0x100, v8
	s_lshl_b32 s18, s94, 7
	s_add_u32 s18, s23, s18
	s_addc_u32 s19, s24, 0
	global_load_dwordx4 v[176:179], v0, s[18:19]
	global_load_dwordx4 v[180:183], v106, s[18:19]
	v_lshlrev_b32_e32 v251, 2, v110
	s_lshl_b32 s18, s94, 2
	s_add_u32 s18, s12, s18
	s_addc_u32 s19, s13, 0
	s_and_saveexec_b64 s[16:17], s[4:5]
	global_load_dwordx4 v[184:187], v251, s[18:19]
	s_or_b64 exec, exec, s[16:17]
	s_waitcnt lgkmcnt(0)
	s_barrier
	s_waitcnt vmcnt(0)
	ds_write_b128 v12, v[82:85]
	v_ashrrev_i32_e32 v12, 31, v13
	v_lshrrev_b32_e32 v12, 29, v12
	v_add_u32_e32 v12, v13, v12
	v_lshrrev_b32_e32 v14, 3, v12
	v_and_b32_e32 v12, -8, v12
	v_sub_u32_e32 v12, v13, v12
	v_mul_lo_u32 v14, v14, s0
	v_lshlrev_b32_e32 v125, 1, v14
	v_lshlrev_b32_e32 v14, 4, v12
	v_add3_u32 v14, s33, v125, v14
	ds_write_b128 v14, v[86:89]
	v_lshrrev_b32_e32 v14, 3, v8
	v_lshlrev_b32_e32 v15, 3, v8
	v_lshrrev_b32_e32 v13, 3, v13
	v_and_b32_e32 v15, 56, v15
	v_mul_lo_u32 v14, v14, s0
	v_mul_lo_u32 v13, v13, s0
	v_lshlrev_b32_e32 v126, 1, v14
	v_lshlrev_b32_e32 v127, 1, v15
	v_and_b32_e32 v230, 1, v215
	v_lshlrev_b32_e32 v230, 3, v230
	v_sub_u32_e32 v230, v127, v230
	v_add_u32_e32 v230, 0x3400, v230
	v_lshlrev_b32_e32 v128, 1, v13
	v_add3_u32 v14, s33, v126, v230
	v_add3_u32 v13, s33, v128, v230
	ds_write2_b64 v14, v[90:91], v[92:93] offset1:2
	ds_write2_b64 v13, v[94:95], v[96:97] offset1:2
	s_and_saveexec_b64 s[6:7], vcc
	s_xor_b64 s[6:7], exec, s[6:7]
	v_mov_b32_e32 v111, v1
	s_andn2_saveexec_b64 s[6:7], s[6:7]
	v_ashrrev_i32_e32 v111, 31, v110
	v_lshl_add_u32 v13, v110, 2, s33
	ds_write_b128 v13, v[98:101] offset:9216
	s_or_b64 exec, exec, s[6:7]
	s_mov_b32 s0, 0xf800000
	v_mul_f32_e32 v13, 0x4f800000, v6
	v_cmp_gt_f32_e32 vcc, s0, v6
	v_lshlrev_b32_e32 v18, 3, v11
	v_lshlrev_b32_e32 v19, 3, v12
	v_cndmask_b32_e32 v6, v6, v13, vcc
	v_sqrt_f32_e32 v13, v6
	v_and_b32_e32 v8, 63, v8
	v_add_u32_e32 v130, s94, v5
	v_cmp_class_f32_e64 s[8:9], v6, v220
	v_add_u32_e32 v11, -1, v13
	v_fma_f32 v12, -v11, v13, v6
	v_cmp_ge_f32_e64 s[6:7], 0, v12
	v_add_u32_e32 v12, 1, v13
	v_mul_u32_u24_e32 v20, 0x48, v3
	v_cndmask_b32_e64 v11, v13, v11, s[6:7]
	v_fma_f32 v13, -v12, v13, v6
	v_cmp_lt_f32_e64 s[6:7], 0, v13
	v_mov_b32_e32 v16, v1
	v_mov_b32_e32 v17, v1
	v_cndmask_b32_e64 v11, v11, v12, s[6:7]
	v_cmp_gt_u32_e64 s[6:7], 32, v8
	v_mul_f32_e32 v12, 0x37800000, v11
	v_cndmask_b32_e32 v11, v11, v12, vcc
	v_cndmask_b32_e64 v9, v9, v10, s[6:7]
	v_add_f32_e32 v7, v7, v9
	v_mul_f32_e32 v9, 0x4f800000, v7
	v_cmp_gt_f32_e32 vcc, s0, v7
	v_cndmask_b32_e64 v6, v11, v6, s[8:9]
	v_mul_f32_e32 v6, 0x3f80068e, v6
	v_cndmask_b32_e32 v7, v7, v9, vcc
	v_sqrt_f32_e32 v9, v7
	v_readlane_b32 s0, v255, 6
	v_lshlrev_b32_e32 v129, 3, v4
	v_or_b32_e32 v131, v130, v3
	v_add_u32_e32 v5, -1, v9
	v_fma_f32 v10, -v5, v9, v7
	v_cmp_ge_f32_e64 s[8:9], 0, v10
	v_add_u32_e32 v10, 1, v9
	v_lshlrev_b32_e32 v112, 2, v4
	v_cndmask_b32_e64 v5, v9, v5, s[8:9]
	v_fma_f32 v9, -v10, v9, v7
	v_cmp_lt_f32_e64 s[8:9], 0, v9
	v_lshl_add_u32 v134, v2, 2, s0
	v_mov_b32_e32 v2, v1
	v_cndmask_b32_e64 v5, v5, v10, s[8:9]
	v_mul_f32_e32 v9, 0x37800000, v5
	v_cndmask_b32_e32 v5, v5, v9, vcc
	v_cmp_class_f32_e32 vcc, v7, v220
	v_cmp_eq_u32_e64 s[8:9], 0, v8
	v_mov_b32_e32 v3, v1
	v_cndmask_b32_e32 v5, v5, v7, vcc
	v_mul_f32_e32 v132, v6, v5
	v_mov_b32_e32 v4, v1
	v_mov_b32_e32 v5, v1
	v_mov_b32_e32 v6, v1
	v_mov_b32_e32 v7, v1
	v_mov_b32_e32 v8, v1
	v_mov_b32_e32 v9, v1
	v_mov_b32_e32 v10, v1
	v_mov_b32_e32 v11, v1
	v_mov_b32_e32 v12, v1
	v_mov_b32_e32 v13, v1
	v_mov_b32_e32 v14, v1
	v_mov_b32_e32 v15, v1
	v_lshlrev_b32_e32 v136, 1, v20
	v_lshlrev_b32_e32 v137, 1, v18
	v_lshlrev_b32_e32 v138, 1, v19
	v_mov_b64_e32 v[32:33], v[16:17]
	s_mov_b32 s28, 0
	v_lshl_add_u64 v[114:115], v[110:111], 2, s[12:13]
	v_or_b32_e32 v133, 31, v130
	v_sub_u32_e32 v135, 0, v129
	v_mov_b32_e32 v139, 0xff800000
	v_mov_b32_e32 v111, 0
	s_mov_b32 s14, s94
	v_mov_b64_e32 v[30:31], v[14:15]
	v_mov_b64_e32 v[28:29], v[12:13]
	v_mov_b64_e32 v[26:27], v[10:11]
	v_mov_b64_e32 v[24:25], v[8:9]
	v_mov_b64_e32 v[22:23], v[6:7]
	v_mov_b64_e32 v[20:21], v[4:5]
	v_mov_b64_e32 v[18:19], v[2:3]
	s_mov_b32 s20, 0
	v_add3_u32 v113, s33, v113, v137
	v_add3_u32 v125, s33, v125, v138
	v_add3_u32 v126, s33, v126, v230
	v_add3_u32 v128, s33, v128, v230
	v_add_u32_e32 v137, 0x5900, v126
	v_add_u32_e32 v138, 0x5900, v128
	v_lshl_add_u32 v135, v110, 2, s33
	v_lshlrev_b32_e32 v34, 1, v129
	v_add3_u32 v212, s33, v136, v34
	v_lshl_add_u32 v213, v112, 2, s33
	v_add_u32_e32 v213, 0x2400, v213
	ds_write_b128 v113, v[176:179] offset:22784
	ds_write_b128 v125, v[180:183] offset:22784
	s_and_saveexec_b64 s[16:17], s[4:5]
	ds_write_b128 v135, v[184:187] offset:32000
	s_or_b64 exec, exec, s[16:17]
	s_lshl_b32 s14, s27, 6
	s_mov_b32 s29, 0
	s_waitcnt lgkmcnt(0)
	s_barrier
	ds_read_b128 v[232:235], v213 offset:0
	ds_read_b128 v[236:239], v213 offset:32
	ds_read_b128 v[240:243], v213 offset:64
	ds_read_b128 v[244:247], v213 offset:96
	ds_read_b128 v[140:143], v213 offset:128
	ds_read_b128 v[144:147], v213 offset:160
	ds_read_b128 v[148:151], v213 offset:192
	ds_read_b128 v[152:155], v213 offset:224
	ds_read_b128 v[156:159], v212 offset:0
	ds_read_b128 v[160:163], v212 offset:4608
	ds_read_b128 v[164:167], v212 offset:32
	ds_read_b128 v[168:171], v212 offset:4640
	ds_read_b128 v[172:175], v212 offset:64
	ds_read_b128 v[208:211], v212 offset:4672
	s_waitcnt lgkmcnt(4)
	v_mfma_f32_32x32x16_bf16 v[50:65], v[156:159], v[66:69], v[232:247]
	v_mfma_f32_32x32x16_bf16 v[34:49], v[160:163], v[66:69], v[140:155]
	ds_read_b128 v[116:119], v212 offset:96
	ds_read_b128 v[120:123], v212 offset:4704
	s_waitcnt lgkmcnt(4)
	v_mfma_f32_32x32x16_bf16 v[50:65], v[164:167], v[70:73], v[50:65]
	v_mfma_f32_32x32x16_bf16 v[34:49], v[168:171], v[70:73], v[34:49]
	s_waitcnt lgkmcnt(2)
	v_mfma_f32_32x32x16_bf16 v[50:65], v[172:175], v[74:77], v[50:65]
	v_mfma_f32_32x32x16_bf16 v[34:49], v[208:211], v[74:77], v[34:49]
	s_waitcnt lgkmcnt(0)
	v_mfma_f32_32x32x16_bf16 v[50:65], v[116:119], v[78:81], v[50:65]
	v_mfma_f32_32x32x16_bf16 v[34:49], v[120:123], v[78:81], v[34:49]
	s_nop 7
	s_nop 3
;     ...
;     for (int it = 0; it < ntiles; ++it) {
;         const int kt = DESC ? ntiles - 1 - it : it, buf = it & 1;
;         if (it + 1 < ntiles) ld_tile(DESC ? kt - 1 : kt + 1);
;         __syncthreads();
;         if ((MODE == 1 || (MODE == 0 && DESC)) && it > 0) {
;             const int* fl = (const int*)(smem0 + SMEM_FLAG) + ((it - 1) & 1) * 8;
;             if ((fl[0] & fl[1] & fl[2] & fl[3] & fl[4] & fl[5] & fl[6] & fl[7]) != 0) break;
;         }
;         const bf16_t* sK = (const bf16_t*)(smem + buf * ATT_BUF); const bf16_t* sV = (const bf16_t*)(smem + buf * ATT_BUF + 13312);
;         const float* sC = (const float*)(smem + buf * ATT_BUF + 22528);
;         bool active = true;
;         if (MODE == 0) active = (64 * kt <= q0 + 32 * w + 31);
;     ...
;                 if (MODE == 0 && (64 * kt + 63 > q0 + 32 * w)) {
; #pragma unroll
;                     for (int mt = 0; mt < 2; ++mt)
; #pragma unroll
;                         for (int qd = 0; qd < 4; ++qd)
; #pragma unroll
;                             for (int e = 0; e < 4; ++e)
;                                 if (64 * kt + 32 * mt + 8 * qd + 4 * h + e > qidx) s4[mt][qd][e] = -INFINITY;
;                 }
.Lfx_even:
	v_mov_b32_e32 v231, 0
	s_cmp_lt_i32 s27, 1
	s_cbranch_scc1 .Lfx_ld_done_0
	s_lshl_b32 s18, s14, 2
	s_add_u32 s18, s12, s18
	s_addc_u32 s19, s13, 0
	global_load_dword v231, v1, s[18:19] offset:-4
	s_add_i32 s48, s14, 0xffffffc0
	s_lshl_b64 s[18:19], s[48:49], 1
	s_add_u32 s18, s25, s18
	s_addc_u32 s19, s26, s19
	global_load_dwordx4 v[90:93], v104, s[18:19]
	global_load_dwordx4 v[94:97], v108, s[18:19]
	s_cmp_lt_i32 s27, 2
	s_cbranch_scc1 .Lfx_ld_done_0
	s_add_i32 s48, s14, 0xffffff80
	s_lshl_b64 s[18:19], s[48:49], 7
	s_add_u32 s18, s23, s18
	s_addc_u32 s19, s24, s19
	global_load_dwordx4 v[82:85], v0, s[18:19]
	global_load_dwordx4 v[86:89], v106, s[18:19]
	s_lshl_b32 s18, s48, 2
	s_add_u32 s18, s12, s18
	s_addc_u32 s19, s13, 0
	s_and_saveexec_b64 s[16:17], s[4:5]
	global_load_dwordx4 v[98:101], v251, s[18:19]
	s_or_b64 exec, exec, s[16:17]
.Lfx_ld_done_0:
	s_waitcnt lgkmcnt(0)
	s_barrier
	s_cmp_eq_u32 s29, 0
	s_cbranch_scc1 .Lfx_even_noexit
	v_mov_b32_e32 v120, 0x122a0
	ds_read_b128 v[116:119], v120
	v_mov_b32_e32 v120, 0x122b0
	ds_read_b128 v[156:159], v120
	s_waitcnt lgkmcnt(0)
	v_and_b32_e32 v116, v117, v116
	v_and_b32_e32 v116, v116, v118
	v_and_b32_e32 v116, v116, v119
	v_and_b32_e32 v116, v116, v156
	v_and_b32_e32 v116, v116, v157
	v_and_b32_e32 v116, v116, v158
	v_and_b32_e32 v116, v116, v159
	v_cmp_ne_u32_e32 vcc, 0, v116
	s_cbranch_vccnz .LBB0_759
.Lfx_even_noexit:
	v_cmp_le_i32_e32 vcc, s14, v133
	s_and_saveexec_b64 s[20:21], vcc
	s_cbranch_execz .Lfx_even_aonly
	ds_read_b128 v[232:235], v213 offset:22784
	ds_read_b128 v[236:239], v213 offset:22816
	ds_read_b128 v[240:243], v213 offset:22848
	ds_read_b128 v[244:247], v213 offset:22880
	ds_read_b128 v[140:143], v213 offset:22912
	ds_read_b128 v[144:147], v213 offset:22944
	ds_read_b128 v[148:151], v213 offset:22976
	ds_read_b128 v[152:155], v213 offset:23008
	ds_read_b128 v[156:159], v212 offset:22784
	ds_read_b128 v[160:163], v212 offset:27392
	ds_read_b128 v[164:167], v212 offset:22816
	ds_read_b128 v[168:171], v212 offset:27424
	ds_read_b128 v[172:175], v212 offset:22848
	ds_read_b128 v[208:211], v212 offset:27456
	s_add_i32 s16, s14, 63
	v_cmp_gt_i32_e32 vcc, s16, v130
	s_and_saveexec_b64 s[16:17], vcc
	s_cbranch_execz .Lfx_nomask_e
	v_sub_u32_e32 v114, v131, v112
	v_subrev_u32_e32 v114, s14, v114
	v_cmp_le_i32_e32 vcc, 0, v114
	s_nop 1
	v_cndmask_b32_e32 v50, v228, v50, vcc
	v_cmp_le_i32_e32 vcc, 1, v114
	s_nop 1
	v_cndmask_b32_e32 v51, v228, v51, vcc
	v_cmp_le_i32_e32 vcc, 2, v114
	s_nop 1
	v_cndmask_b32_e32 v52, v228, v52, vcc
	v_cmp_le_i32_e32 vcc, 3, v114
	s_nop 1
	v_cndmask_b32_e32 v53, v228, v53, vcc
	v_cmp_le_i32_e32 vcc, 8, v114
	s_nop 1
	v_cndmask_b32_e32 v54, v228, v54, vcc
	v_cmp_le_i32_e32 vcc, 9, v114
	s_nop 1
	v_cndmask_b32_e32 v55, v228, v55, vcc
	v_cmp_le_i32_e32 vcc, 10, v114
	s_nop 1
	v_cndmask_b32_e32 v56, v228, v56, vcc
	v_cmp_le_i32_e32 vcc, 11, v114
	s_nop 1
	v_cndmask_b32_e32 v57, v228, v57, vcc
	v_cmp_le_i32_e32 vcc, 16, v114
	s_nop 1
	v_cndmask_b32_e32 v58, v228, v58, vcc
	v_cmp_le_i32_e32 vcc, 17, v114
	s_nop 1
	v_cndmask_b32_e32 v59, v228, v59, vcc
	v_cmp_le_i32_e32 vcc, 18, v114
	s_nop 1
	v_cndmask_b32_e32 v60, v228, v60, vcc
	v_cmp_le_i32_e32 vcc, 19, v114
	s_nop 1
	v_cndmask_b32_e32 v61, v228, v61, vcc
	v_cmp_le_i32_e32 vcc, 24, v114
	s_nop 1
	v_cndmask_b32_e32 v62, v228, v62, vcc
	v_cmp_le_i32_e32 vcc, 25, v114
	s_nop 1
	v_cndmask_b32_e32 v63, v228, v63, vcc
	v_cmp_le_i32_e32 vcc, 26, v114
	s_nop 1
	v_cndmask_b32_e32 v64, v228, v64, vcc
	v_cmp_le_i32_e32 vcc, 27, v114
	s_nop 1
	v_cndmask_b32_e32 v65, v228, v65, vcc
	v_cmp_le_i32_e32 vcc, 32, v114
	s_nop 1
	v_cndmask_b32_e32 v34, v228, v34, vcc
	v_cmp_le_i32_e32 vcc, 33, v114
	s_nop 1
	v_cndmask_b32_e32 v35, v228, v35, vcc
	v_cmp_le_i32_e32 vcc, 34, v114
	s_nop 1
	v_cndmask_b32_e32 v36, v228, v36, vcc
	v_cmp_le_i32_e32 vcc, 35, v114
	s_nop 1
	v_cndmask_b32_e32 v37, v228, v37, vcc
	v_cmp_le_i32_e32 vcc, 40, v114
	s_nop 1
	v_cndmask_b32_e32 v38, v228, v38, vcc
	v_cmp_le_i32_e32 vcc, 41, v114
	s_nop 1
	v_cndmask_b32_e32 v39, v228, v39, vcc
	v_cmp_le_i32_e32 vcc, 42, v114
	s_nop 1
	v_cndmask_b32_e32 v40, v228, v40, vcc
	v_cmp_le_i32_e32 vcc, 43, v114
	s_nop 1
	v_cndmask_b32_e32 v41, v228, v41, vcc
	v_cmp_le_i32_e32 vcc, 48, v114
	s_nop 1
	v_cndmask_b32_e32 v42, v228, v42, vcc
	v_cmp_le_i32_e32 vcc, 49, v114
	s_nop 1
	v_cndmask_b32_e32 v43, v228, v43, vcc
	v_cmp_le_i32_e32 vcc, 50, v114
	s_nop 1
	v_cndmask_b32_e32 v44, v228, v44, vcc
	v_cmp_le_i32_e32 vcc, 51, v114
	s_nop 1
	v_cndmask_b32_e32 v45, v228, v45, vcc
	v_cmp_le_i32_e32 vcc, 56, v114
	s_nop 1
	v_cndmask_b32_e32 v46, v228, v46, vcc
	v_cmp_le_i32_e32 vcc, 57, v114
	s_nop 1
	v_cndmask_b32_e32 v47, v228, v47, vcc
	v_cmp_le_i32_e32 vcc, 58, v114
	s_nop 1
	v_cndmask_b32_e32 v48, v228, v48, vcc
	v_cmp_le_i32_e32 vcc, 59, v114
	s_nop 1
	v_cndmask_b32_e32 v49, v228, v49, vcc
;     ...
;             for (int s = 0; s < NKS; ++s) {
;                 const bf16x8 k0 = *(const bf16x8*)(sK + r * KS + 16 * s + 8 * h), k1 = *(const bf16x8*)(sK + (32 + r) * KS + 16 * s + 8 * h);
;     ...
;                 float mx = fmaxf(s4[0][0].x, s4[1][0].x);
; #pragma unroll
;                 for (int qd = 0; qd < 4; ++qd) {
;                     mx = fmaxf(fmaxf(mx, s4[0][qd].y), s4[1][qd].y);
;                     mx = fmaxf(fmaxf(mx, s4[0][qd].z), s4[1][qd].z);
;                     mx = fmaxf(fmaxf(mx, s4[0][qd].w), s4[1][qd].w);
;                     if (qd < 3) mx = fmaxf(fmaxf(mx, s4[0][qd + 1].x), s4[1][qd + 1].x);
;                 }
;                 mx = xhalf_max(mx);
;                 const float mn = fmaxf(m, mx), alpha = fexp2(m - mn);
;                 m = mn;
;                 f32x4 ps4 = {0.f, 0.f, 0.f, 0.f};
;                 const float nmn = -mn;
;                 const f32x4 nm4 = {nmn, nmn, nmn, nmn};
;                 if (__builtin_amdgcn_ballot_w64(alpha != 1.f) != 0) { o0 *= alpha; o1 *= alpha; }
; #pragma unroll
;                 for (int s2 = 0; s2 < 4; ++s2) {
;                     const int mt = s2 >> 1, s = s2 & 1;
;                     f32x4 da = s4[mt][2 * s] + nm4, db = s4[mt][2 * s + 1] + nm4;
;                     da.x = fexp2(da.x); da.y = fexp2(da.y); da.z = fexp2(da.z); da.w = fexp2(da.w);
;                     db.x = fexp2(db.x); db.y = fexp2(db.y); db.z = fexp2(db.z); db.w = fexp2(db.w);
;                     ps4 += da; ps4 += db;
;                     u32x4 pp;
;                     pp.x = pk2(da.x, da.y); pp.y = pk2(da.z, da.w); pp.z = pk2(db.x, db.y); pp.w = pk2(db.z, db.w);
;                     const bf16x8 pfr = __builtin_bit_cast(bf16x8, pp);
;                     const s16x4 a0 = *(const s16x4*)(sV + r * LS + 16 * s2 + 4 * h), a1 = *(const s16x4*)(sV + r * LS + 16 * s2 + 8 + 4 * h);
;                     const s16x4 b0 = *(const s16x4*)(sV + (32 + r) * LS + 16 * s2 + 4 * h), b1 = *(const s16x4*)(sV + (32 + r) * LS + 16 * s2 + 8 + 4 * h);
;                     const bf16x8 v0 = __builtin_shufflevector(a0, a1, 0, 1, 2, 3, 4, 5, 6, 7), v1 = __builtin_shufflevector(b0, b1, 0, 1, 2, 3, 4, 5, 6, 7);
;                     o0 = MFMA32(v0, pfr, o0);
;                     o1 = MFMA32(v1, pfr, o1);
;                 }
;                 lsum = lsum * alpha + ((ps4.x + ps4.y) + (ps4.z + ps4.w));
.Lfx_nomask_e:
	s_or_b64 exec, exec, s[16:17]
	v_max3_f32 v248, v50, v51, v52
	v_max3_f32 v249, v53, v54, v55
	v_max3_f32 v250, v56, v57, v58
	v_max3_f32 v105, v59, v60, v61
	v_max3_f32 v248, v248, v62, v63
	v_max3_f32 v249, v249, v64, v65
	v_max3_f32 v250, v250, v34, v35
	v_max3_f32 v105, v105, v36, v37
	s_waitcnt lgkmcnt(4)
	v_mfma_f32_32x32x16_bf16 v[176:191], v[156:159], v[66:69], v[232:247]
	v_mfma_f32_32x32x16_bf16 v[192:207], v[160:163], v[66:69], v[140:155]
	ds_read_b128 v[116:119], v212 offset:22880
	ds_read_b128 v[120:123], v212 offset:27488
	v_max3_f32 v248, v248, v38, v39
	v_max3_f32 v249, v249, v40, v41
	v_max3_f32 v250, v250, v42, v43
	v_max3_f32 v105, v105, v44, v45
	v_max3_f32 v248, v248, v46, v47
	v_max3_f32 v249, v249, v48, v49
	v_max3_f32 v248, v248, v249, v250
	v_max_f32_e32 v248, v248, v105
	v_mov_b32_e32 v249, v248
	s_nop 1
	v_permlane32_swap_b32_e32 v248, v249
	s_waitcnt lgkmcnt(4)
	v_mfma_f32_32x32x16_bf16 v[176:191], v[164:167], v[70:73], v[176:191]
	v_mfma_f32_32x32x16_bf16 v[192:207], v[168:171], v[70:73], v[192:207]
	ds_read_b128 v[156:159], v212 offset:13312
	ds_read_b128 v[160:163], v212 offset:17920
	v_max3_f32 v248, v139, v248, v249
	v_sub_f32_e32 v216, v139, v248
	v_exp_f32_e32 v216, v216
	v_mov_b32_e32 v139, v248
	s_waitcnt lgkmcnt(4)
	v_mfma_f32_32x32x16_bf16 v[176:191], v[172:175], v[74:77], v[176:191]
	v_mfma_f32_32x32x16_bf16 v[192:207], v[208:211], v[74:77], v[192:207]
	ds_read_b128 v[164:167], v212 offset:13344
	ds_read_b128 v[168:171], v212 offset:17952
	v_cmp_neq_f32_e32 vcc, 1.0, v216
	s_cbranch_vccz .Lfx_noresc_e
	v_pk_mul_f32 v[32:33], v[32:33], v[216:217] op_sel_hi:[1,0]
	v_pk_mul_f32 v[30:31], v[30:31], v[216:217] op_sel_hi:[1,0]
	v_pk_mul_f32 v[28:29], v[28:29], v[216:217] op_sel_hi:[1,0]
	v_pk_mul_f32 v[26:27], v[26:27], v[216:217] op_sel_hi:[1,0]
	v_pk_mul_f32 v[24:25], v[24:25], v[216:217] op_sel_hi:[1,0]
	v_pk_mul_f32 v[22:23], v[22:23], v[216:217] op_sel_hi:[1,0]
	v_pk_mul_f32 v[20:21], v[20:21], v[216:217] op_sel_hi:[1,0]
	v_pk_mul_f32 v[18:19], v[18:19], v[216:217] op_sel_hi:[1,0]
	v_pk_mul_f32 v[16:17], v[16:17], v[216:217] op_sel_hi:[1,0]
	v_pk_mul_f32 v[14:15], v[14:15], v[216:217] op_sel_hi:[1,0]
	v_pk_mul_f32 v[12:13], v[12:13], v[216:217] op_sel_hi:[1,0]
	v_pk_mul_f32 v[10:11], v[10:11], v[216:217] op_sel_hi:[1,0]
	v_pk_mul_f32 v[8:9], v[8:9], v[216:217] op_sel_hi:[1,0]
	v_pk_mul_f32 v[6:7], v[6:7], v[216:217] op_sel_hi:[1,0]
	v_pk_mul_f32 v[4:5], v[4:5], v[216:217] op_sel_hi:[1,0]
	v_pk_mul_f32 v[2:3], v[2:3], v[216:217] op_sel_hi:[1,0]
.Lfx_noresc_e:
	v_sub_f32_e32 v50, v50, v248
	v_sub_f32_e32 v51, v51, v248
	v_sub_f32_e32 v52, v52, v248
	v_sub_f32_e32 v53, v53, v248
	v_sub_f32_e32 v54, v54, v248
	v_sub_f32_e32 v55, v55, v248
	v_sub_f32_e32 v56, v56, v248
	v_sub_f32_e32 v57, v57, v248
	s_waitcnt lgkmcnt(4)
	v_mfma_f32_32x32x16_bf16 v[176:191], v[116:119], v[78:81], v[176:191]
	v_mfma_f32_32x32x16_bf16 v[192:207], v[120:123], v[78:81], v[192:207]
	ds_read_b128 v[172:175], v212 offset:13376
	ds_read_b128 v[208:211], v212 offset:17984
	v_exp_f32_e32 v50, v50
	v_exp_f32_e32 v51, v51
	v_exp_f32_e32 v52, v52
	v_exp_f32_e32 v53, v53
	v_exp_f32_e32 v54, v54
	v_exp_f32_e32 v55, v55
	v_exp_f32_e32 v56, v56
	v_exp_f32_e32 v57, v57
	v_cvt_pk_bf16_f32 v232, v50, v51
	v_cvt_pk_bf16_f32 v233, v52, v53
	v_cvt_pk_bf16_f32 v234, v54, v55
	v_cvt_pk_bf16_f32 v235, v56, v57
	v_sub_f32_e32 v58, v58, v248
	v_sub_f32_e32 v59, v59, v248
	v_sub_f32_e32 v60, v60, v248
	v_sub_f32_e32 v61, v61, v248
	v_sub_f32_e32 v62, v62, v248
	v_sub_f32_e32 v63, v63, v248
	v_sub_f32_e32 v64, v64, v248
	v_sub_f32_e32 v65, v65, v248
	s_waitcnt lgkmcnt(4)
	v_mfma_f32_32x32x16_bf16 v[18:33], v[156:159], v[232:235], v[18:33]
	v_mfma_f32_32x32x16_bf16 v[2:17], v[160:163], v[232:235], v[2:17]
	ds_read_b128 v[116:119], v212 offset:13408
	ds_read_b128 v[120:123], v212 offset:18016
	v_exp_f32_e32 v58, v58
	v_exp_f32_e32 v59, v59
	v_exp_f32_e32 v60, v60
	v_exp_f32_e32 v61, v61
	v_exp_f32_e32 v62, v62
	v_exp_f32_e32 v63, v63
	v_exp_f32_e32 v64, v64
	v_exp_f32_e32 v65, v65
	v_add_f32_e32 v249, v50, v51
	v_add_f32_e32 v250, v52, v53
	v_add_f32_e32 v105, v54, v55
	v_add_f32_e32 v107, v56, v57
	v_add_f32_e32 v249, v249, v250
	v_add_f32_e32 v105, v105, v107
	v_add_f32_e32 v109, v249, v105
	v_cvt_pk_bf16_f32 v236, v58, v59
	v_cvt_pk_bf16_f32 v237, v60, v61
	v_cvt_pk_bf16_f32 v238, v62, v63
	v_cvt_pk_bf16_f32 v239, v64, v65
	v_sub_f32_e32 v34, v34, v248
	v_sub_f32_e32 v35, v35, v248
	v_sub_f32_e32 v36, v36, v248
	v_sub_f32_e32 v37, v37, v248
	v_sub_f32_e32 v38, v38, v248
	v_sub_f32_e32 v39, v39, v248
	v_sub_f32_e32 v40, v40, v248
	v_sub_f32_e32 v41, v41, v248
	s_waitcnt lgkmcnt(4)
	v_mfma_f32_32x32x16_bf16 v[18:33], v[164:167], v[236:239], v[18:33]
	v_mfma_f32_32x32x16_bf16 v[2:17], v[168:171], v[236:239], v[2:17]
	v_exp_f32_e32 v34, v34
	v_exp_f32_e32 v35, v35
	v_exp_f32_e32 v36, v36
	v_exp_f32_e32 v37, v37
	v_exp_f32_e32 v38, v38
	v_exp_f32_e32 v39, v39
	v_exp_f32_e32 v40, v40
	v_exp_f32_e32 v41, v41
	v_add_f32_e32 v249, v58, v59
	v_add_f32_e32 v250, v60, v61
	v_add_f32_e32 v105, v62, v63
	v_add_f32_e32 v107, v64, v65
	v_add_f32_e32 v249, v249, v250
	v_add_f32_e32 v105, v105, v107
	v_add_f32_e32 v249, v249, v105
	v_add_f32_e32 v109, v109, v249
	v_cvt_pk_bf16_f32 v240, v34, v35
	v_cvt_pk_bf16_f32 v241, v36, v37
	v_cvt_pk_bf16_f32 v242, v38, v39
	v_cvt_pk_bf16_f32 v243, v40, v41
	v_sub_f32_e32 v42, v42, v248
	v_sub_f32_e32 v43, v43, v248
	v_sub_f32_e32 v44, v44, v248
	v_sub_f32_e32 v45, v45, v248
	v_sub_f32_e32 v46, v46, v248
	v_sub_f32_e32 v47, v47, v248
	v_sub_f32_e32 v48, v48, v248
	v_sub_f32_e32 v49, v49, v248
	s_waitcnt lgkmcnt(2)
	v_mfma_f32_32x32x16_bf16 v[18:33], v[172:175], v[240:243], v[18:33]
	v_mfma_f32_32x32x16_bf16 v[2:17], v[208:211], v[240:243], v[2:17]
	v_exp_f32_e32 v42, v42
	v_exp_f32_e32 v43, v43
	v_exp_f32_e32 v44, v44
	v_exp_f32_e32 v45, v45
	v_exp_f32_e32 v46, v46
	v_exp_f32_e32 v47, v47
	v_exp_f32_e32 v48, v48
	v_exp_f32_e32 v49, v49
	v_add_f32_e32 v249, v34, v35
	v_add_f32_e32 v250, v36, v37
	v_add_f32_e32 v105, v38, v39
	v_add_f32_e32 v107, v40, v41
	v_add_f32_e32 v249, v249, v250
	v_add_f32_e32 v105, v105, v107
	v_add_f32_e32 v249, v249, v105
	v_add_f32_e32 v109, v109, v249
	v_cvt_pk_bf16_f32 v232, v42, v43
	v_cvt_pk_bf16_f32 v233, v44, v45
	v_cvt_pk_bf16_f32 v234, v46, v47
	v_cvt_pk_bf16_f32 v235, v48, v49
	v_add_f32_e32 v249, v42, v43
	v_add_f32_e32 v250, v44, v45
	v_add_f32_e32 v105, v46, v47
	v_add_f32_e32 v107, v48, v49
	s_waitcnt lgkmcnt(0)
	v_mfma_f32_32x32x16_bf16 v[18:33], v[116:119], v[232:235], v[18:33]
	v_mfma_f32_32x32x16_bf16 v[2:17], v[120:123], v[232:235], v[2:17]
	v_add_f32_e32 v249, v249, v250
	v_add_f32_e32 v105, v105, v107
	v_add_f32_e32 v249, v249, v105
	v_add_f32_e32 v109, v109, v249
	v_fma_f32 v111, v111, v216, v109
	s_or_b64 exec, exec, s[20:21]
	s_branch .Lfx_even_flags
;     ...
;     for (int it = 0; it < ntiles; ++it) {
;         const int kt = DESC ? ntiles - 1 - it : it, buf = it & 1;
;         if (it + 1 < ntiles) ld_tile(DESC ? kt - 1 : kt + 1);
;         __syncthreads();
;         if ((MODE == 1 || (MODE == 0 && DESC)) && it > 0) {
;             const int* fl = (const int*)(smem0 + SMEM_FLAG) + ((it - 1) & 1) * 8;
;             if ((fl[0] & fl[1] & fl[2] & fl[3] & fl[4] & fl[5] & fl[6] & fl[7]) != 0) break;
;         }
;         const bf16_t* sK = (const bf16_t*)(smem + buf * ATT_BUF); const bf16_t* sV = (const bf16_t*)(smem + buf * ATT_BUF + 13312);
;         const float* sC = (const float*)(smem + buf * ATT_BUF + 22528);
;         bool active = true;
;         if (MODE == 0) active = (64 * kt <= q0 + 32 * w + 31);
;     ...
;         if (MODE == 1) {
;             const int done = (__builtin_amdgcn_ballot_w64(R != 0.f) == 0) ? 1 : 0;
;             if (lane == 0) ((int*)(smem0 + SMEM_FLAG))[(it & 1) * 8 + hf * 4 + w] = done;
;         }
;         if (MODE == 0 && DESC) {
;             const float ncl = (kt > 0) ? cdec[64 * kt - 1] : 0.f;
;             const bool live = !(qn + ncl - m < -152.f);
;             const int done = (__builtin_amdgcn_ballot_w64(live) == 0) ? 1 : 0;
;             if (lane == 0) ((int*)(smem0 + SMEM_FLAG))[(it & 1) * 8 + hf * 4 + w] = done;
;         }
;         if (it + 1 < ntiles) st_tile(buf ^ 1);
.Lfx_even_aonly:
	s_or_b64 exec, exec, s[20:21]
	ds_read_b128 v[232:235], v213 offset:22784
	ds_read_b128 v[236:239], v213 offset:22816
	ds_read_b128 v[240:243], v213 offset:22848
	ds_read_b128 v[244:247], v213 offset:22880
	ds_read_b128 v[140:143], v213 offset:22912
	ds_read_b128 v[144:147], v213 offset:22944
	ds_read_b128 v[148:151], v213 offset:22976
	ds_read_b128 v[152:155], v213 offset:23008
	ds_read_b128 v[156:159], v212 offset:22784
	ds_read_b128 v[160:163], v212 offset:27392
	ds_read_b128 v[164:167], v212 offset:22816
	ds_read_b128 v[168:171], v212 offset:27424
	ds_read_b128 v[172:175], v212 offset:22848
	ds_read_b128 v[208:211], v212 offset:27456
	s_waitcnt lgkmcnt(4)
	v_mfma_f32_32x32x16_bf16 v[176:191], v[156:159], v[66:69], v[232:247]
	v_mfma_f32_32x32x16_bf16 v[192:207], v[160:163], v[66:69], v[140:155]
	ds_read_b128 v[116:119], v212 offset:22880
	ds_read_b128 v[120:123], v212 offset:27488
	s_waitcnt lgkmcnt(4)
	v_mfma_f32_32x32x16_bf16 v[176:191], v[164:167], v[70:73], v[176:191]
	v_mfma_f32_32x32x16_bf16 v[192:207], v[168:171], v[70:73], v[192:207]
	s_waitcnt lgkmcnt(2)
	v_mfma_f32_32x32x16_bf16 v[176:191], v[172:175], v[74:77], v[176:191]
	v_mfma_f32_32x32x16_bf16 v[192:207], v[208:211], v[74:77], v[192:207]
	s_waitcnt lgkmcnt(0)
	v_mfma_f32_32x32x16_bf16 v[176:191], v[116:119], v[78:81], v[176:191]
	v_mfma_f32_32x32x16_bf16 v[192:207], v[120:123], v[78:81], v[192:207]
.Lfx_even_flags:
	s_waitcnt vmcnt(0)
	v_add_f32_e32 v249, v132, v231
	v_sub_f32_e32 v249, v249, v139
	s_mov_b32 s18, 0xc3180000
	v_cmp_ngt_f32_e32 vcc, s18, v249
	s_and_saveexec_b64 s[18:19], s[8:9]
	s_cmp_eq_u64 vcc, 0
	s_cselect_b64 s[16:17], -1, 0
	v_cndmask_b32_e64 v249, 0, 1, s[16:17]
	ds_write_b32 v134, v249
	s_or_b64 exec, exec, s[18:19]
	s_cmp_lt_i32 s27, 1
	s_cbranch_scc1 .Lfx_wr_done_0
	ds_write2_b64 v137, v[90:91], v[92:93] offset1:2
	ds_write2_b64 v138, v[94:95], v[96:97] offset1:2
	s_cmp_lt_i32 s27, 2
	s_cbranch_scc1 .Lfx_wr_done_0
	ds_write_b128 v113, v[82:85]
	ds_write_b128 v125, v[86:89]
	s_and_saveexec_b64 s[16:17], s[4:5]
	ds_write_b128 v135, v[98:101] offset:9216
	s_or_b64 exec, exec, s[16:17]
.Lfx_wr_done_0:
	s_mov_b32 s29, 1
	s_add_i32 s27, s27, -1
	s_add_i32 s14, s14, 0xffffffc0
	v_mov_b32_e32 v231, 0
	s_cmp_lt_i32 s27, 1
	s_cbranch_scc1 .Lfx_ld_done_1
	s_lshl_b32 s18, s14, 2
	s_add_u32 s18, s12, s18
	s_addc_u32 s19, s13, 0
	global_load_dword v231, v1, s[18:19] offset:-4
	s_add_i32 s48, s14, 0xffffffc0
	s_lshl_b64 s[18:19], s[48:49], 1
	s_add_u32 s18, s25, s18
	s_addc_u32 s19, s26, s19
	global_load_dwordx4 v[90:93], v104, s[18:19]
	global_load_dwordx4 v[94:97], v108, s[18:19]
	s_cmp_lt_i32 s27, 2
	s_cbranch_scc1 .Lfx_ld_done_1
	s_add_i32 s48, s14, 0xffffff80
	s_lshl_b64 s[18:19], s[48:49], 7
	s_add_u32 s18, s23, s18
	s_addc_u32 s19, s24, s19
	global_load_dwordx4 v[82:85], v0, s[18:19]
	global_load_dwordx4 v[86:89], v106, s[18:19]
	s_lshl_b32 s18, s48, 2
	s_add_u32 s18, s12, s18
	s_addc_u32 s19, s13, 0
	s_and_saveexec_b64 s[16:17], s[4:5]
	global_load_dwordx4 v[98:101], v251, s[18:19]
	s_or_b64 exec, exec, s[16:17]
.Lfx_ld_done_1:
	s_waitcnt lgkmcnt(0)
	s_barrier
	v_mov_b32_e32 v120, 0x12280
	ds_read_b128 v[116:119], v120
	v_mov_b32_e32 v120, 0x12290
	ds_read_b128 v[156:159], v120
	s_waitcnt lgkmcnt(0)
	v_and_b32_e32 v116, v117, v116
	v_and_b32_e32 v116, v116, v118
	v_and_b32_e32 v116, v116, v119
	v_and_b32_e32 v116, v116, v156
	v_and_b32_e32 v116, v116, v157
	v_and_b32_e32 v116, v116, v158
	v_and_b32_e32 v116, v116, v159
	v_cmp_ne_u32_e32 vcc, 0, v116
	s_cbranch_vccnz .LBB0_759
	s_cmp_eq_u32 s27, 0
	s_cbranch_scc1 .Lfx_last
	ds_read_b128 v[232:235], v213 offset:0
	ds_read_b128 v[236:239], v213 offset:32
	ds_read_b128 v[240:243], v213 offset:64
	ds_read_b128 v[244:247], v213 offset:96
	ds_read_b128 v[140:143], v213 offset:128
	ds_read_b128 v[144:147], v213 offset:160
	ds_read_b128 v[148:151], v213 offset:192
	ds_read_b128 v[152:155], v213 offset:224
	ds_read_b128 v[156:159], v212 offset:0
	ds_read_b128 v[160:163], v212 offset:4608
	ds_read_b128 v[164:167], v212 offset:32
	ds_read_b128 v[168:171], v212 offset:4640
	ds_read_b128 v[172:175], v212 offset:64
	ds_read_b128 v[208:211], v212 offset:4672
	s_add_i32 s16, s14, 63
	v_cmp_gt_i32_e32 vcc, s16, v130
	s_and_saveexec_b64 s[16:17], vcc
	s_cbranch_execz .Lfx_nomask_o
	v_sub_u32_e32 v114, v131, v112
	v_subrev_u32_e32 v114, s14, v114
	v_cmp_le_i32_e32 vcc, 0, v114
	s_nop 1
	v_cndmask_b32_e32 v176, v228, v176, vcc
	v_cmp_le_i32_e32 vcc, 1, v114
	s_nop 1
	v_cndmask_b32_e32 v177, v228, v177, vcc
	v_cmp_le_i32_e32 vcc, 2, v114
	s_nop 1
	v_cndmask_b32_e32 v178, v228, v178, vcc
	v_cmp_le_i32_e32 vcc, 3, v114
	s_nop 1
	v_cndmask_b32_e32 v179, v228, v179, vcc
	v_cmp_le_i32_e32 vcc, 8, v114
	s_nop 1
	v_cndmask_b32_e32 v180, v228, v180, vcc
	v_cmp_le_i32_e32 vcc, 9, v114
	s_nop 1
	v_cndmask_b32_e32 v181, v228, v181, vcc
	v_cmp_le_i32_e32 vcc, 10, v114
	s_nop 1
	v_cndmask_b32_e32 v182, v228, v182, vcc
	v_cmp_le_i32_e32 vcc, 11, v114
	s_nop 1
	v_cndmask_b32_e32 v183, v228, v183, vcc
	v_cmp_le_i32_e32 vcc, 16, v114
	s_nop 1
	v_cndmask_b32_e32 v184, v228, v184, vcc
	v_cmp_le_i32_e32 vcc, 17, v114
	s_nop 1
	v_cndmask_b32_e32 v185, v228, v185, vcc
	v_cmp_le_i32_e32 vcc, 18, v114
	s_nop 1
	v_cndmask_b32_e32 v186, v228, v186, vcc
	v_cmp_le_i32_e32 vcc, 19, v114
	s_nop 1
	v_cndmask_b32_e32 v187, v228, v187, vcc
	v_cmp_le_i32_e32 vcc, 24, v114
	s_nop 1
	v_cndmask_b32_e32 v188, v228, v188, vcc
	v_cmp_le_i32_e32 vcc, 25, v114
	s_nop 1
	v_cndmask_b32_e32 v189, v228, v189, vcc
	v_cmp_le_i32_e32 vcc, 26, v114
	s_nop 1
	v_cndmask_b32_e32 v190, v228, v190, vcc
	v_cmp_le_i32_e32 vcc, 27, v114
	s_nop 1
	v_cndmask_b32_e32 v191, v228, v191, vcc
	v_cmp_le_i32_e32 vcc, 32, v114
	s_nop 1
	v_cndmask_b32_e32 v192, v228, v192, vcc
	v_cmp_le_i32_e32 vcc, 33, v114
	s_nop 1
	v_cndmask_b32_e32 v193, v228, v193, vcc
	v_cmp_le_i32_e32 vcc, 34, v114
	s_nop 1
	v_cndmask_b32_e32 v194, v228, v194, vcc
	v_cmp_le_i32_e32 vcc, 35, v114
	s_nop 1
	v_cndmask_b32_e32 v195, v228, v195, vcc
	v_cmp_le_i32_e32 vcc, 40, v114
	s_nop 1
	v_cndmask_b32_e32 v196, v228, v196, vcc
	v_cmp_le_i32_e32 vcc, 41, v114
	s_nop 1
	v_cndmask_b32_e32 v197, v228, v197, vcc
	v_cmp_le_i32_e32 vcc, 42, v114
	s_nop 1
	v_cndmask_b32_e32 v198, v228, v198, vcc
	v_cmp_le_i32_e32 vcc, 43, v114
	s_nop 1
	v_cndmask_b32_e32 v199, v228, v199, vcc
	v_cmp_le_i32_e32 vcc, 48, v114
	s_nop 1
	v_cndmask_b32_e32 v200, v228, v200, vcc
	v_cmp_le_i32_e32 vcc, 49, v114
	s_nop 1
	v_cndmask_b32_e32 v201, v228, v201, vcc
	v_cmp_le_i32_e32 vcc, 50, v114
	s_nop 1
	v_cndmask_b32_e32 v202, v228, v202, vcc
	v_cmp_le_i32_e32 vcc, 51, v114
	s_nop 1
	v_cndmask_b32_e32 v203, v228, v203, vcc
	v_cmp_le_i32_e32 vcc, 56, v114
	s_nop 1
	v_cndmask_b32_e32 v204, v228, v204, vcc
	v_cmp_le_i32_e32 vcc, 57, v114
	s_nop 1
	v_cndmask_b32_e32 v205, v228, v205, vcc
	v_cmp_le_i32_e32 vcc, 58, v114
	s_nop 1
	v_cndmask_b32_e32 v206, v228, v206, vcc
	v_cmp_le_i32_e32 vcc, 59, v114
	s_nop 1
	v_cndmask_b32_e32 v207, v228, v207, vcc
;     ...
;             for (int s = 0; s < NKS; ++s) {
;                 const bf16x8 k0 = *(const bf16x8*)(sK + r * KS + 16 * s + 8 * h), k1 = *(const bf16x8*)(sK + (32 + r) * KS + 16 * s + 8 * h);
;     ...
;                 float mx = fmaxf(s4[0][0].x, s4[1][0].x);
; #pragma unroll
;                 for (int qd = 0; qd < 4; ++qd) {
;                     mx = fmaxf(fmaxf(mx, s4[0][qd].y), s4[1][qd].y);
;                     mx = fmaxf(fmaxf(mx, s4[0][qd].z), s4[1][qd].z);
;                     mx = fmaxf(fmaxf(mx, s4[0][qd].w), s4[1][qd].w);
;                     if (qd < 3) mx = fmaxf(fmaxf(mx, s4[0][qd + 1].x), s4[1][qd + 1].x);
;                 }
;                 mx = xhalf_max(mx);
;                 const float mn = fmaxf(m, mx), alpha = fexp2(m - mn);
;                 m = mn;
;                 f32x4 ps4 = {0.f, 0.f, 0.f, 0.f};
;                 const float nmn = -mn;
;                 const f32x4 nm4 = {nmn, nmn, nmn, nmn};
;                 if (__builtin_amdgcn_ballot_w64(alpha != 1.f) != 0) { o0 *= alpha; o1 *= alpha; }
; #pragma unroll
;                 for (int s2 = 0; s2 < 4; ++s2) {
;                     const int mt = s2 >> 1, s = s2 & 1;
;                     f32x4 da = s4[mt][2 * s] + nm4, db = s4[mt][2 * s + 1] + nm4;
;                     da.x = fexp2(da.x); da.y = fexp2(da.y); da.z = fexp2(da.z); da.w = fexp2(da.w);
;                     db.x = fexp2(db.x); db.y = fexp2(db.y); db.z = fexp2(db.z); db.w = fexp2(db.w);
;                     ps4 += da; ps4 += db;
;                     u32x4 pp;
;                     pp.x = pk2(da.x, da.y); pp.y = pk2(da.z, da.w); pp.z = pk2(db.x, db.y); pp.w = pk2(db.z, db.w);
;                     const bf16x8 pfr = __builtin_bit_cast(bf16x8, pp);
;                     const s16x4 a0 = *(const s16x4*)(sV + r * LS + 16 * s2 + 4 * h), a1 = *(const s16x4*)(sV + r * LS + 16 * s2 + 8 + 4 * h);
;                     const s16x4 b0 = *(const s16x4*)(sV + (32 + r) * LS + 16 * s2 + 4 * h), b1 = *(const s16x4*)(sV + (32 + r) * LS + 16 * s2 + 8 + 4 * h);
;                     const bf16x8 v0 = __builtin_shufflevector(a0, a1, 0, 1, 2, 3, 4, 5, 6, 7), v1 = __builtin_shufflevector(b0, b1, 0, 1, 2, 3, 4, 5, 6, 7);
;                     o0 = MFMA32(v0, pfr, o0);
;                     o1 = MFMA32(v1, pfr, o1);
;                 }
;                 lsum = lsum * alpha + ((ps4.x + ps4.y) + (ps4.z + ps4.w));
.Lfx_nomask_o:
	s_or_b64 exec, exec, s[16:17]
	v_max3_f32 v248, v176, v177, v178
	v_max3_f32 v249, v179, v180, v181
	v_max3_f32 v250, v182, v183, v184
	v_max3_f32 v105, v185, v186, v187
	v_max3_f32 v248, v248, v188, v189
	v_max3_f32 v249, v249, v190, v191
	v_max3_f32 v250, v250, v192, v193
	v_max3_f32 v105, v105, v194, v195
	s_waitcnt lgkmcnt(4)
	v_mfma_f32_32x32x16_bf16 v[50:65], v[156:159], v[66:69], v[232:247]
	v_mfma_f32_32x32x16_bf16 v[34:49], v[160:163], v[66:69], v[140:155]
	ds_read_b128 v[116:119], v212 offset:96
	ds_read_b128 v[120:123], v212 offset:4704
	v_max3_f32 v248, v248, v196, v197
	v_max3_f32 v249, v249, v198, v199
	v_max3_f32 v250, v250, v200, v201
	v_max3_f32 v105, v105, v202, v203
	v_max3_f32 v248, v248, v204, v205
	v_max3_f32 v249, v249, v206, v207
	v_max3_f32 v248, v248, v249, v250
	v_max_f32_e32 v248, v248, v105
	v_mov_b32_e32 v249, v248
	s_nop 1
	v_permlane32_swap_b32_e32 v248, v249
	s_waitcnt lgkmcnt(4)
	v_mfma_f32_32x32x16_bf16 v[50:65], v[164:167], v[70:73], v[50:65]
	v_mfma_f32_32x32x16_bf16 v[34:49], v[168:171], v[70:73], v[34:49]
	ds_read_b128 v[156:159], v212 offset:36096
	ds_read_b128 v[160:163], v212 offset:40704
	v_max3_f32 v248, v139, v248, v249
	v_sub_f32_e32 v216, v139, v248
	v_exp_f32_e32 v216, v216
	v_mov_b32_e32 v139, v248
	s_waitcnt lgkmcnt(4)
	v_mfma_f32_32x32x16_bf16 v[50:65], v[172:175], v[74:77], v[50:65]
	v_mfma_f32_32x32x16_bf16 v[34:49], v[208:211], v[74:77], v[34:49]
	ds_read_b128 v[164:167], v212 offset:36128
	ds_read_b128 v[168:171], v212 offset:40736
	v_cmp_neq_f32_e32 vcc, 1.0, v216
	s_cbranch_vccz .Lfx_noresc_o
	v_pk_mul_f32 v[32:33], v[32:33], v[216:217] op_sel_hi:[1,0]
	v_pk_mul_f32 v[30:31], v[30:31], v[216:217] op_sel_hi:[1,0]
	v_pk_mul_f32 v[28:29], v[28:29], v[216:217] op_sel_hi:[1,0]
	v_pk_mul_f32 v[26:27], v[26:27], v[216:217] op_sel_hi:[1,0]
	v_pk_mul_f32 v[24:25], v[24:25], v[216:217] op_sel_hi:[1,0]
	v_pk_mul_f32 v[22:23], v[22:23], v[216:217] op_sel_hi:[1,0]
	v_pk_mul_f32 v[20:21], v[20:21], v[216:217] op_sel_hi:[1,0]
	v_pk_mul_f32 v[18:19], v[18:19], v[216:217] op_sel_hi:[1,0]
	v_pk_mul_f32 v[16:17], v[16:17], v[216:217] op_sel_hi:[1,0]
	v_pk_mul_f32 v[14:15], v[14:15], v[216:217] op_sel_hi:[1,0]
	v_pk_mul_f32 v[12:13], v[12:13], v[216:217] op_sel_hi:[1,0]
	v_pk_mul_f32 v[10:11], v[10:11], v[216:217] op_sel_hi:[1,0]
	v_pk_mul_f32 v[8:9], v[8:9], v[216:217] op_sel_hi:[1,0]
	v_pk_mul_f32 v[6:7], v[6:7], v[216:217] op_sel_hi:[1,0]
	v_pk_mul_f32 v[4:5], v[4:5], v[216:217] op_sel_hi:[1,0]
	v_pk_mul_f32 v[2:3], v[2:3], v[216:217] op_sel_hi:[1,0]
.Lfx_noresc_o:
	v_sub_f32_e32 v176, v176, v248
	v_sub_f32_e32 v177, v177, v248
	v_sub_f32_e32 v178, v178, v248
	v_sub_f32_e32 v179, v179, v248
	v_sub_f32_e32 v180, v180, v248
	v_sub_f32_e32 v181, v181, v248
	v_sub_f32_e32 v182, v182, v248
	v_sub_f32_e32 v183, v183, v248
	s_waitcnt lgkmcnt(4)
	v_mfma_f32_32x32x16_bf16 v[50:65], v[116:119], v[78:81], v[50:65]
	v_mfma_f32_32x32x16_bf16 v[34:49], v[120:123], v[78:81], v[34:49]
	ds_read_b128 v[172:175], v212 offset:36160
	ds_read_b128 v[208:211], v212 offset:40768
	v_exp_f32_e32 v176, v176
	v_exp_f32_e32 v177, v177
	v_exp_f32_e32 v178, v178
	v_exp_f32_e32 v179, v179
	v_exp_f32_e32 v180, v180
	v_exp_f32_e32 v181, v181
	v_exp_f32_e32 v182, v182
	v_exp_f32_e32 v183, v183
	v_cvt_pk_bf16_f32 v232, v176, v177
	v_cvt_pk_bf16_f32 v233, v178, v179
	v_cvt_pk_bf16_f32 v234, v180, v181
	v_cvt_pk_bf16_f32 v235, v182, v183
	v_sub_f32_e32 v184, v184, v248
	v_sub_f32_e32 v185, v185, v248
	v_sub_f32_e32 v186, v186, v248
	v_sub_f32_e32 v187, v187, v248
	v_sub_f32_e32 v188, v188, v248
	v_sub_f32_e32 v189, v189, v248
	v_sub_f32_e32 v190, v190, v248
	v_sub_f32_e32 v191, v191, v248
	s_waitcnt lgkmcnt(4)
	v_mfma_f32_32x32x16_bf16 v[18:33], v[156:159], v[232:235], v[18:33]
	v_mfma_f32_32x32x16_bf16 v[2:17], v[160:163], v[232:235], v[2:17]
	ds_read_b128 v[116:119], v212 offset:36192
	ds_read_b128 v[120:123], v212 offset:40800
	v_exp_f32_e32 v184, v184
	v_exp_f32_e32 v185, v185
	v_exp_f32_e32 v186, v186
	v_exp_f32_e32 v187, v187
	v_exp_f32_e32 v188, v188
	v_exp_f32_e32 v189, v189
	v_exp_f32_e32 v190, v190
	v_exp_f32_e32 v191, v191
	v_add_f32_e32 v249, v176, v177
	v_add_f32_e32 v250, v178, v179
	v_add_f32_e32 v105, v180, v181
	v_add_f32_e32 v107, v182, v183
	v_add_f32_e32 v249, v249, v250
	v_add_f32_e32 v105, v105, v107
	v_add_f32_e32 v109, v249, v105
	v_cvt_pk_bf16_f32 v236, v184, v185
	v_cvt_pk_bf16_f32 v237, v186, v187
	v_cvt_pk_bf16_f32 v238, v188, v189
	v_cvt_pk_bf16_f32 v239, v190, v191
	v_sub_f32_e32 v192, v192, v248
	v_sub_f32_e32 v193, v193, v248
	v_sub_f32_e32 v194, v194, v248
	v_sub_f32_e32 v195, v195, v248
	v_sub_f32_e32 v196, v196, v248
	v_sub_f32_e32 v197, v197, v248
	v_sub_f32_e32 v198, v198, v248
	v_sub_f32_e32 v199, v199, v248
	s_waitcnt lgkmcnt(4)
	v_mfma_f32_32x32x16_bf16 v[18:33], v[164:167], v[236:239], v[18:33]
	v_mfma_f32_32x32x16_bf16 v[2:17], v[168:171], v[236:239], v[2:17]
	v_exp_f32_e32 v192, v192
	v_exp_f32_e32 v193, v193
	v_exp_f32_e32 v194, v194
	v_exp_f32_e32 v195, v195
	v_exp_f32_e32 v196, v196
	v_exp_f32_e32 v197, v197
	v_exp_f32_e32 v198, v198
	v_exp_f32_e32 v199, v199
	v_add_f32_e32 v249, v184, v185
	v_add_f32_e32 v250, v186, v187
	v_add_f32_e32 v105, v188, v189
	v_add_f32_e32 v107, v190, v191
	v_add_f32_e32 v249, v249, v250
	v_add_f32_e32 v105, v105, v107
	v_add_f32_e32 v249, v249, v105
	v_add_f32_e32 v109, v109, v249
	v_cvt_pk_bf16_f32 v240, v192, v193
	v_cvt_pk_bf16_f32 v241, v194, v195
	v_cvt_pk_bf16_f32 v242, v196, v197
	v_cvt_pk_bf16_f32 v243, v198, v199
	v_sub_f32_e32 v200, v200, v248
	v_sub_f32_e32 v201, v201, v248
	v_sub_f32_e32 v202, v202, v248
	v_sub_f32_e32 v203, v203, v248
	v_sub_f32_e32 v204, v204, v248
	v_sub_f32_e32 v205, v205, v248
	v_sub_f32_e32 v206, v206, v248
	v_sub_f32_e32 v207, v207, v248
	s_waitcnt lgkmcnt(2)
; DI float fexp2(float x) { return __builtin_amdgcn_exp2f(x); }
;     ...
;                 float mx = fmaxf(s4[0][0].x, s4[1][0].x);
; #pragma unroll
;                 for (int qd = 0; qd < 4; ++qd) {
;                     mx = fmaxf(fmaxf(mx, s4[0][qd].y), s4[1][qd].y);
;                     mx = fmaxf(fmaxf(mx, s4[0][qd].z), s4[1][qd].z);
;                     mx = fmaxf(fmaxf(mx, s4[0][qd].w), s4[1][qd].w);
;                     if (qd < 3) mx = fmaxf(fmaxf(mx, s4[0][qd + 1].x), s4[1][qd + 1].x);
;                 }
;                 mx = xhalf_max(mx);
;                 const float mn = fmaxf(m, mx), alpha = fexp2(m - mn);
;                 m = mn;
;                 f32x4 ps4 = {0.f, 0.f, 0.f, 0.f};
;                 const float nmn = -mn;
;                 const f32x4 nm4 = {nmn, nmn, nmn, nmn};
;                 if (__builtin_amdgcn_ballot_w64(alpha != 1.f) != 0) { o0 *= alpha; o1 *= alpha; }
; #pragma unroll
;                 for (int s2 = 0; s2 < 4; ++s2) {
;                     const int mt = s2 >> 1, s = s2 & 1;
;                     f32x4 da = s4[mt][2 * s] + nm4, db = s4[mt][2 * s + 1] + nm4;
;                     da.x = fexp2(da.x); da.y = fexp2(da.y); da.z = fexp2(da.z); da.w = fexp2(da.w);
;                     db.x = fexp2(db.x); db.y = fexp2(db.y); db.z = fexp2(db.z); db.w = fexp2(db.w);
;                     ps4 += da; ps4 += db;
;                     u32x4 pp;
;                     pp.x = pk2(da.x, da.y); pp.y = pk2(da.z, da.w); pp.z = pk2(db.x, db.y); pp.w = pk2(db.z, db.w);
;                     const bf16x8 pfr = __builtin_bit_cast(bf16x8, pp);
;                     const s16x4 a0 = *(const s16x4*)(sV + r * LS + 16 * s2 + 4 * h), a1 = *(const s16x4*)(sV + r * LS + 16 * s2 + 8 + 4 * h);
;     ...
;         if (MODE == 1) {
;             const int done = (__builtin_amdgcn_ballot_w64(R != 0.f) == 0) ? 1 : 0;
;             if (lane == 0) ((int*)(smem0 + SMEM_FLAG))[(it & 1) * 8 + hf * 4 + w] = done;
;         }
;         if (MODE == 0 && DESC) {
;             const float ncl = (kt > 0) ? cdec[64 * kt - 1] : 0.f;
;             const bool live = !(qn + ncl - m < -152.f);
;             const int done = (__builtin_amdgcn_ballot_w64(live) == 0) ? 1 : 0;
;             if (lane == 0) ((int*)(smem0 + SMEM_FLAG))[(it & 1) * 8 + hf * 4 + w] = done;
;         }
;         if (it + 1 < ntiles) st_tile(buf ^ 1);
	v_mfma_f32_32x32x16_bf16 v[18:33], v[172:175], v[240:243], v[18:33]
	v_mfma_f32_32x32x16_bf16 v[2:17], v[208:211], v[240:243], v[2:17]
	v_exp_f32_e32 v200, v200
	v_exp_f32_e32 v201, v201
	v_exp_f32_e32 v202, v202
	v_exp_f32_e32 v203, v203
	v_exp_f32_e32 v204, v204
	v_exp_f32_e32 v205, v205
	v_exp_f32_e32 v206, v206
	v_exp_f32_e32 v207, v207
	v_add_f32_e32 v249, v192, v193
	v_add_f32_e32 v250, v194, v195
	v_add_f32_e32 v105, v196, v197
	v_add_f32_e32 v107, v198, v199
	v_add_f32_e32 v249, v249, v250
	v_add_f32_e32 v105, v105, v107
	v_add_f32_e32 v249, v249, v105
	v_add_f32_e32 v109, v109, v249
	v_cvt_pk_bf16_f32 v232, v200, v201
	v_cvt_pk_bf16_f32 v233, v202, v203
	v_cvt_pk_bf16_f32 v234, v204, v205
	v_cvt_pk_bf16_f32 v235, v206, v207
	v_add_f32_e32 v249, v200, v201
	v_add_f32_e32 v250, v202, v203
	v_add_f32_e32 v105, v204, v205
	v_add_f32_e32 v107, v206, v207
	s_waitcnt lgkmcnt(0)
	v_mfma_f32_32x32x16_bf16 v[18:33], v[116:119], v[232:235], v[18:33]
	v_mfma_f32_32x32x16_bf16 v[2:17], v[120:123], v[232:235], v[2:17]
	v_add_f32_e32 v249, v249, v250
	v_add_f32_e32 v105, v105, v107
	v_add_f32_e32 v249, v249, v105
	v_add_f32_e32 v109, v109, v249
	v_fma_f32 v111, v111, v216, v109
	s_waitcnt vmcnt(0)
	v_add_f32_e32 v249, v132, v231
	v_sub_f32_e32 v249, v249, v139
	s_mov_b32 s18, 0xc3180000
	v_cmp_ngt_f32_e32 vcc, s18, v249
	s_and_saveexec_b64 s[18:19], s[8:9]
	s_cmp_eq_u64 vcc, 0
	s_cselect_b64 s[16:17], -1, 0
	v_cndmask_b32_e64 v249, 0, 1, s[16:17]
	ds_write_b32 v134, v249 offset:32
	s_or_b64 exec, exec, s[18:19]
	s_cmp_lt_i32 s27, 1
	s_cbranch_scc1 .Lfx_wr_done_1
	ds_write2_b64 v126, v[90:91], v[92:93] offset1:2
	ds_write2_b64 v128, v[94:95], v[96:97] offset1:2
	s_cmp_lt_i32 s27, 2
	s_cbranch_scc1 .Lfx_wr_done_1
	ds_write_b128 v113, v[82:85] offset:22784
	ds_write_b128 v125, v[86:89] offset:22784
	s_and_saveexec_b64 s[16:17], s[4:5]
	ds_write_b128 v135, v[98:101] offset:32000
	s_or_b64 exec, exec, s[16:17]
.Lfx_wr_done_1:
	s_add_i32 s27, s27, -1
	s_add_i32 s14, s14, 0xffffffc0
	s_branch .Lfx_even
.Lfx_last:
	ds_read_b128 v[156:159], v212 offset:36096
	ds_read_b128 v[160:163], v212 offset:40704
	ds_read_b128 v[164:167], v212 offset:36128
	ds_read_b128 v[168:171], v212 offset:40736
	ds_read_b128 v[172:175], v212 offset:36160
	ds_read_b128 v[208:211], v212 offset:40768
	ds_read_b128 v[116:119], v212 offset:36192
	ds_read_b128 v[120:123], v212 offset:40800
	s_add_i32 s16, s14, 63
	v_cmp_gt_i32_e32 vcc, s16, v130
	s_and_saveexec_b64 s[16:17], vcc
	s_cbranch_execz .Lfx_nomask_f
	v_sub_u32_e32 v114, v131, v112
	v_subrev_u32_e32 v114, s14, v114
	v_cmp_le_i32_e32 vcc, 0, v114
	s_nop 1
	v_cndmask_b32_e32 v176, v228, v176, vcc
	v_cmp_le_i32_e32 vcc, 1, v114
	s_nop 1
	v_cndmask_b32_e32 v177, v228, v177, vcc
	v_cmp_le_i32_e32 vcc, 2, v114
	s_nop 1
	v_cndmask_b32_e32 v178, v228, v178, vcc
	v_cmp_le_i32_e32 vcc, 3, v114
	s_nop 1
	v_cndmask_b32_e32 v179, v228, v179, vcc
	v_cmp_le_i32_e32 vcc, 8, v114
	s_nop 1
	v_cndmask_b32_e32 v180, v228, v180, vcc
	v_cmp_le_i32_e32 vcc, 9, v114
	s_nop 1
	v_cndmask_b32_e32 v181, v228, v181, vcc
	v_cmp_le_i32_e32 vcc, 10, v114
	s_nop 1
	v_cndmask_b32_e32 v182, v228, v182, vcc
	v_cmp_le_i32_e32 vcc, 11, v114
	s_nop 1
	v_cndmask_b32_e32 v183, v228, v183, vcc
	v_cmp_le_i32_e32 vcc, 16, v114
	s_nop 1
	v_cndmask_b32_e32 v184, v228, v184, vcc
	v_cmp_le_i32_e32 vcc, 17, v114
	s_nop 1
	v_cndmask_b32_e32 v185, v228, v185, vcc
	v_cmp_le_i32_e32 vcc, 18, v114
	s_nop 1
	v_cndmask_b32_e32 v186, v228, v186, vcc
	v_cmp_le_i32_e32 vcc, 19, v114
	s_nop 1
	v_cndmask_b32_e32 v187, v228, v187, vcc
	v_cmp_le_i32_e32 vcc, 24, v114
	s_nop 1
	v_cndmask_b32_e32 v188, v228, v188, vcc
	v_cmp_le_i32_e32 vcc, 25, v114
	s_nop 1
	v_cndmask_b32_e32 v189, v228, v189, vcc
	v_cmp_le_i32_e32 vcc, 26, v114
	s_nop 1
	v_cndmask_b32_e32 v190, v228, v190, vcc
	v_cmp_le_i32_e32 vcc, 27, v114
	s_nop 1
	v_cndmask_b32_e32 v191, v228, v191, vcc
	v_cmp_le_i32_e32 vcc, 32, v114
	s_nop 1
	v_cndmask_b32_e32 v192, v228, v192, vcc
	v_cmp_le_i32_e32 vcc, 33, v114
	s_nop 1
	v_cndmask_b32_e32 v193, v228, v193, vcc
	v_cmp_le_i32_e32 vcc, 34, v114
	s_nop 1
	v_cndmask_b32_e32 v194, v228, v194, vcc
	v_cmp_le_i32_e32 vcc, 35, v114
	s_nop 1
	v_cndmask_b32_e32 v195, v228, v195, vcc
	v_cmp_le_i32_e32 vcc, 40, v114
	s_nop 1
	v_cndmask_b32_e32 v196, v228, v196, vcc
	v_cmp_le_i32_e32 vcc, 41, v114
	s_nop 1
	v_cndmask_b32_e32 v197, v228, v197, vcc
	v_cmp_le_i32_e32 vcc, 42, v114
	s_nop 1
	v_cndmask_b32_e32 v198, v228, v198, vcc
	v_cmp_le_i32_e32 vcc, 43, v114
	s_nop 1
	v_cndmask_b32_e32 v199, v228, v199, vcc
	v_cmp_le_i32_e32 vcc, 48, v114
	s_nop 1
	v_cndmask_b32_e32 v200, v228, v200, vcc
	v_cmp_le_i32_e32 vcc, 49, v114
	s_nop 1
	v_cndmask_b32_e32 v201, v228, v201, vcc
	v_cmp_le_i32_e32 vcc, 50, v114
	s_nop 1
	v_cndmask_b32_e32 v202, v228, v202, vcc
	v_cmp_le_i32_e32 vcc, 51, v114
	s_nop 1
	v_cndmask_b32_e32 v203, v228, v203, vcc
	v_cmp_le_i32_e32 vcc, 56, v114
	s_nop 1
	v_cndmask_b32_e32 v204, v228, v204, vcc
	v_cmp_le_i32_e32 vcc, 57, v114
	s_nop 1
	v_cndmask_b32_e32 v205, v228, v205, vcc
	v_cmp_le_i32_e32 vcc, 58, v114
	s_nop 1
	v_cndmask_b32_e32 v206, v228, v206, vcc
	v_cmp_le_i32_e32 vcc, 59, v114
	s_nop 1
	v_cndmask_b32_e32 v207, v228, v207, vcc
; DI unsigned pk2(float a, float b) { f32x2 v = {a, b}; return __builtin_bit_cast(unsigned, __builtin_convertvector(v, bf2_t)); }
; #define MFMA32(a, b, c) __builtin_amdgcn_mfma_f32_32x32x16_bf16((a), (b), (c), 0, 0, 0)
;     ...
;                 float mx = fmaxf(s4[0][0].x, s4[1][0].x);
; #pragma unroll
;                 for (int qd = 0; qd < 4; ++qd) {
;                     mx = fmaxf(fmaxf(mx, s4[0][qd].y), s4[1][qd].y);
;                     mx = fmaxf(fmaxf(mx, s4[0][qd].z), s4[1][qd].z);
;                     mx = fmaxf(fmaxf(mx, s4[0][qd].w), s4[1][qd].w);
;                     if (qd < 3) mx = fmaxf(fmaxf(mx, s4[0][qd + 1].x), s4[1][qd + 1].x);
;                 }
;                 mx = xhalf_max(mx);
;                 const float mn = fmaxf(m, mx), alpha = fexp2(m - mn);
;                 m = mn;
;                 f32x4 ps4 = {0.f, 0.f, 0.f, 0.f};
;                 const float nmn = -mn;
;                 const f32x4 nm4 = {nmn, nmn, nmn, nmn};
;                 if (__builtin_amdgcn_ballot_w64(alpha != 1.f) != 0) { o0 *= alpha; o1 *= alpha; }
; #pragma unroll
;                 for (int s2 = 0; s2 < 4; ++s2) {
;                     const int mt = s2 >> 1, s = s2 & 1;
;                     f32x4 da = s4[mt][2 * s] + nm4, db = s4[mt][2 * s + 1] + nm4;
;                     da.x = fexp2(da.x); da.y = fexp2(da.y); da.z = fexp2(da.z); da.w = fexp2(da.w);
;                     db.x = fexp2(db.x); db.y = fexp2(db.y); db.z = fexp2(db.z); db.w = fexp2(db.w);
;                     ps4 += da; ps4 += db;
;                     u32x4 pp;
;                     pp.x = pk2(da.x, da.y); pp.y = pk2(da.z, da.w); pp.z = pk2(db.x, db.y); pp.w = pk2(db.z, db.w);
;                     const bf16x8 pfr = __builtin_bit_cast(bf16x8, pp);
;                     const s16x4 a0 = *(const s16x4*)(sV + r * LS + 16 * s2 + 4 * h), a1 = *(const s16x4*)(sV + r * LS + 16 * s2 + 8 + 4 * h);
;                     const s16x4 b0 = *(const s16x4*)(sV + (32 + r) * LS + 16 * s2 + 4 * h), b1 = *(const s16x4*)(sV + (32 + r) * LS + 16 * s2 + 8 + 4 * h);
;                     const bf16x8 v0 = __builtin_shufflevector(a0, a1, 0, 1, 2, 3, 4, 5, 6, 7), v1 = __builtin_shufflevector(b0, b1, 0, 1, 2, 3, 4, 5, 6, 7);
;                     o0 = MFMA32(v0, pfr, o0);
;                     o1 = MFMA32(v1, pfr, o1);
;                 }
;                 lsum = lsum * alpha + ((ps4.x + ps4.y) + (ps4.z + ps4.w));
.Lfx_nomask_f:
	s_or_b64 exec, exec, s[16:17]
	v_max3_f32 v248, v176, v177, v178
	v_max3_f32 v249, v179, v180, v181
	v_max3_f32 v250, v182, v183, v184
	v_max3_f32 v105, v185, v186, v187
	v_max3_f32 v248, v248, v188, v189
	v_max3_f32 v249, v249, v190, v191
	v_max3_f32 v250, v250, v192, v193
	v_max3_f32 v105, v105, v194, v195
	v_max3_f32 v248, v248, v196, v197
	v_max3_f32 v249, v249, v198, v199
	v_max3_f32 v250, v250, v200, v201
	v_max3_f32 v105, v105, v202, v203
	v_max3_f32 v248, v248, v204, v205
	v_max3_f32 v249, v249, v206, v207
	v_max3_f32 v248, v248, v249, v250
	v_max_f32_e32 v248, v248, v105
	v_mov_b32_e32 v249, v248
	s_nop 1
	v_permlane32_swap_b32_e32 v248, v249
	v_max3_f32 v248, v139, v248, v249
	v_sub_f32_e32 v216, v139, v248
	v_exp_f32_e32 v216, v216
	v_mov_b32_e32 v139, v248
	v_cmp_neq_f32_e32 vcc, 1.0, v216
	s_cbranch_vccz .Lfx_noresc_f
	v_pk_mul_f32 v[32:33], v[32:33], v[216:217] op_sel_hi:[1,0]
	v_pk_mul_f32 v[30:31], v[30:31], v[216:217] op_sel_hi:[1,0]
	v_pk_mul_f32 v[28:29], v[28:29], v[216:217] op_sel_hi:[1,0]
	v_pk_mul_f32 v[26:27], v[26:27], v[216:217] op_sel_hi:[1,0]
	v_pk_mul_f32 v[24:25], v[24:25], v[216:217] op_sel_hi:[1,0]
	v_pk_mul_f32 v[22:23], v[22:23], v[216:217] op_sel_hi:[1,0]
	v_pk_mul_f32 v[20:21], v[20:21], v[216:217] op_sel_hi:[1,0]
	v_pk_mul_f32 v[18:19], v[18:19], v[216:217] op_sel_hi:[1,0]
	v_pk_mul_f32 v[16:17], v[16:17], v[216:217] op_sel_hi:[1,0]
	v_pk_mul_f32 v[14:15], v[14:15], v[216:217] op_sel_hi:[1,0]
	v_pk_mul_f32 v[12:13], v[12:13], v[216:217] op_sel_hi:[1,0]
	v_pk_mul_f32 v[10:11], v[10:11], v[216:217] op_sel_hi:[1,0]
	v_pk_mul_f32 v[8:9], v[8:9], v[216:217] op_sel_hi:[1,0]
	v_pk_mul_f32 v[6:7], v[6:7], v[216:217] op_sel_hi:[1,0]
	v_pk_mul_f32 v[4:5], v[4:5], v[216:217] op_sel_hi:[1,0]
	v_pk_mul_f32 v[2:3], v[2:3], v[216:217] op_sel_hi:[1,0]
.Lfx_noresc_f:
	v_sub_f32_e32 v176, v176, v248
	v_sub_f32_e32 v177, v177, v248
	v_sub_f32_e32 v178, v178, v248
	v_sub_f32_e32 v179, v179, v248
	v_sub_f32_e32 v180, v180, v248
	v_sub_f32_e32 v181, v181, v248
	v_sub_f32_e32 v182, v182, v248
	v_sub_f32_e32 v183, v183, v248
	v_exp_f32_e32 v176, v176
	v_exp_f32_e32 v177, v177
	v_exp_f32_e32 v178, v178
	v_exp_f32_e32 v179, v179
	v_exp_f32_e32 v180, v180
	v_exp_f32_e32 v181, v181
	v_exp_f32_e32 v182, v182
	v_exp_f32_e32 v183, v183
	v_cvt_pk_bf16_f32 v232, v176, v177
	v_cvt_pk_bf16_f32 v233, v178, v179
	v_cvt_pk_bf16_f32 v234, v180, v181
	v_cvt_pk_bf16_f32 v235, v182, v183
	v_sub_f32_e32 v184, v184, v248
	v_sub_f32_e32 v185, v185, v248
	v_sub_f32_e32 v186, v186, v248
	v_sub_f32_e32 v187, v187, v248
	v_sub_f32_e32 v188, v188, v248
	v_sub_f32_e32 v189, v189, v248
	v_sub_f32_e32 v190, v190, v248
	v_sub_f32_e32 v191, v191, v248
	s_waitcnt lgkmcnt(6)
	v_mfma_f32_32x32x16_bf16 v[18:33], v[156:159], v[232:235], v[18:33]
	v_mfma_f32_32x32x16_bf16 v[2:17], v[160:163], v[232:235], v[2:17]
	v_exp_f32_e32 v184, v184
	v_exp_f32_e32 v185, v185
	v_exp_f32_e32 v186, v186
	v_exp_f32_e32 v187, v187
	v_exp_f32_e32 v188, v188
	v_exp_f32_e32 v189, v189
	v_exp_f32_e32 v190, v190
	v_exp_f32_e32 v191, v191
	v_add_f32_e32 v249, v176, v177
	v_add_f32_e32 v250, v178, v179
	v_add_f32_e32 v105, v180, v181
	v_add_f32_e32 v107, v182, v183
	v_add_f32_e32 v249, v249, v250
	v_add_f32_e32 v105, v105, v107
	v_add_f32_e32 v109, v249, v105
	v_cvt_pk_bf16_f32 v236, v184, v185
	v_cvt_pk_bf16_f32 v237, v186, v187
	v_cvt_pk_bf16_f32 v238, v188, v189
	v_cvt_pk_bf16_f32 v239, v190, v191
	v_sub_f32_e32 v192, v192, v248
	v_sub_f32_e32 v193, v193, v248
	v_sub_f32_e32 v194, v194, v248
	v_sub_f32_e32 v195, v195, v248
	v_sub_f32_e32 v196, v196, v248
	v_sub_f32_e32 v197, v197, v248
	v_sub_f32_e32 v198, v198, v248
	v_sub_f32_e32 v199, v199, v248
	s_waitcnt lgkmcnt(4)
	v_mfma_f32_32x32x16_bf16 v[18:33], v[164:167], v[236:239], v[18:33]
	v_mfma_f32_32x32x16_bf16 v[2:17], v[168:171], v[236:239], v[2:17]
	v_exp_f32_e32 v192, v192
	v_exp_f32_e32 v193, v193
	v_exp_f32_e32 v194, v194
	v_exp_f32_e32 v195, v195
	v_exp_f32_e32 v196, v196
	v_exp_f32_e32 v197, v197
	v_exp_f32_e32 v198, v198
	v_exp_f32_e32 v199, v199
	v_add_f32_e32 v249, v184, v185
	v_add_f32_e32 v250, v186, v187
	v_add_f32_e32 v105, v188, v189
	v_add_f32_e32 v107, v190, v191
	v_add_f32_e32 v249, v249, v250
	v_add_f32_e32 v105, v105, v107
	v_add_f32_e32 v249, v249, v105
	v_add_f32_e32 v109, v109, v249
	v_cvt_pk_bf16_f32 v240, v192, v193
	v_cvt_pk_bf16_f32 v241, v194, v195
	v_cvt_pk_bf16_f32 v242, v196, v197
	v_cvt_pk_bf16_f32 v243, v198, v199
	v_sub_f32_e32 v200, v200, v248
	v_sub_f32_e32 v201, v201, v248
	v_sub_f32_e32 v202, v202, v248
	v_sub_f32_e32 v203, v203, v248
	v_sub_f32_e32 v204, v204, v248
	v_sub_f32_e32 v205, v205, v248
	v_sub_f32_e32 v206, v206, v248
	v_sub_f32_e32 v207, v207, v248
	s_waitcnt lgkmcnt(2)
	v_mfma_f32_32x32x16_bf16 v[18:33], v[172:175], v[240:243], v[18:33]
	v_mfma_f32_32x32x16_bf16 v[2:17], v[208:211], v[240:243], v[2:17]
	v_exp_f32_e32 v200, v200
	v_exp_f32_e32 v201, v201
	v_exp_f32_e32 v202, v202
	v_exp_f32_e32 v203, v203
	v_exp_f32_e32 v204, v204
	v_exp_f32_e32 v205, v205
	v_exp_f32_e32 v206, v206
	v_exp_f32_e32 v207, v207
	v_add_f32_e32 v249, v192, v193
	v_add_f32_e32 v250, v194, v195
	v_add_f32_e32 v105, v196, v197
	v_add_f32_e32 v107, v198, v199
	v_add_f32_e32 v249, v249, v250
	v_add_f32_e32 v105, v105, v107
	v_add_f32_e32 v249, v249, v105
	v_add_f32_e32 v109, v109, v249
	v_cvt_pk_bf16_f32 v232, v200, v201
	v_cvt_pk_bf16_f32 v233, v202, v203
	v_cvt_pk_bf16_f32 v234, v204, v205
	v_cvt_pk_bf16_f32 v235, v206, v207
	v_add_f32_e32 v249, v200, v201
	v_add_f32_e32 v250, v202, v203
	v_add_f32_e32 v105, v204, v205
	v_add_f32_e32 v107, v206, v207
	s_waitcnt lgkmcnt(0)
	v_mfma_f32_32x32x16_bf16 v[18:33], v[116:119], v[232:235], v[18:33]
	v_mfma_f32_32x32x16_bf16 v[2:17], v[120:123], v[232:235], v[2:17]
	v_add_f32_e32 v249, v249, v250
	v_add_f32_e32 v105, v105, v107
	v_add_f32_e32 v249, v249, v105
	v_add_f32_e32 v109, v109, v249
	v_fma_f32 v111, v111, v216, v109
; DI unsigned pk2(float a, float b) { f32x2 v = {a, b}; return __builtin_bit_cast(unsigned, __builtin_convertvector(v, bf2_t)); }
; DI float bflo(unsigned u) { return __uint_as_float(u << 16); }
; DI float bfhi(unsigned u) { return __uint_as_float(u & 0xffff0000u); }
; DI float xhalf_other(float x, int h) { auto r = __builtin_amdgcn_permlane32_swap(__float_as_uint(x), __float_as_uint(x), false, false); return h ? __uint_as_float(r[0]) : __uint_as_float(r[1]); }
;     ...
;     if (MODE != 1) {
;         const float lt = lsum + xhalf_other(lsum, h), inv = __builtin_amdgcn_rcpf(lt);
;         o0 *= inv; o1 *= inv;
;     }
;     bf16_t* yrow = yb + (size_t)(32 * w + r) * 1024 + 4 * h;
;     const bf16_t* grow = gt + (size_t)(32 * w + r) * 1024 + 4 * h;
;     u32x2 gv[2][4];
; #pragma unroll
;     for (int nt = 0; nt < 2; ++nt)
; #pragma unroll
;         for (int qd = 0; qd < 4; ++qd) gv[nt][qd] = *(const u32x2*)(grow + 32 * nt + 8 * qd);
; #pragma unroll
;     for (int nt = 0; nt < 2; ++nt)
; #pragma unroll
;         for (int qd = 0; qd < 4; ++qd) {
;             const u32x2 g = gv[nt][qd];
;             const f32x16& o = nt ? o1 : o0;
;             u32x2 v;
;             v.x = pk2(o[4 * qd] * bflo(g.x), o[4 * qd + 1] * bfhi(g.x));
;             v.y = pk2(o[4 * qd + 2] * bflo(g.y), o[4 * qd + 3] * bfhi(g.y));
;             *(u32x2*)(yrow + 32 * nt + 8 * qd) = v;
;         }
.LBB0_759:
.LBB0_770:
	s_mov_b32 s57, s49
	s_lshl_b64 s[4:5], s[94:95], 11
	s_lshl_b64 s[8:9], s[56:57], 24
	s_or_b64 s[4:5], s[4:5], s[8:9]
	s_add_u32 s8, s69, s4
	s_addc_u32 s9, s60, s5
	s_lshl_b32 s12, s79, 7
	s_add_u32 s8, s8, s12
	s_addc_u32 s9, s9, 0
	v_lshlrev_b64 v[42:43], 11, v[102:103]
	v_lshl_add_u64 v[34:35], s[8:9], 0, v[42:43]
	v_lshlrev_b32_e32 v0, 1, v112
	v_lshl_add_u64 v[34:35], v[34:35], 0, v[0:1]
	global_load_dwordx2 v[44:45], v[34:35], off offset:1024
	global_load_dwordx2 v[46:47], v[34:35], off offset:1040
	global_load_dwordx2 v[48:49], v[34:35], off offset:1056
	global_load_dwordx2 v[50:51], v[34:35], off offset:1072
	global_load_dwordx2 v[40:41], v[34:35], off offset:1088
	global_load_dwordx2 v[38:39], v[34:35], off offset:1104
	global_load_dwordx2 v[36:37], v[34:35], off offset:1120
	s_nop 0
	global_load_dwordx2 v[34:35], v[34:35], off offset:1136
	v_mov_b32_e32 v52, v111
	v_mov_b32_e32 v53, v111
	s_nop 1
	v_permlane32_swap_b32_e32 v52, v53
	v_cndmask_b32_e64 v52, v52, v53, s[6:7]
	v_add_f32_e32 v52, v111, v52
	v_rcp_f32_e32 v52, v52
	s_add_u32 s4, s61, s4
	s_addc_u32 s5, s70, s5
	s_add_u32 s4, s4, s12
	s_addc_u32 s5, s5, 0
	v_pk_mul_f32 v[20:21], v[20:21], v[52:53] op_sel_hi:[1,0]
	v_pk_mul_f32 v[18:19], v[18:19], v[52:53] op_sel_hi:[1,0]
	v_lshl_add_u64 v[42:43], s[4:5], 0, v[42:43]
	v_pk_mul_f32 v[32:33], v[32:33], v[52:53] op_sel_hi:[1,0]
	v_pk_mul_f32 v[30:31], v[30:31], v[52:53] op_sel_hi:[1,0]
	v_pk_mul_f32 v[28:29], v[28:29], v[52:53] op_sel_hi:[1,0]
	v_pk_mul_f32 v[26:27], v[26:27], v[52:53] op_sel_hi:[1,0]
	v_pk_mul_f32 v[24:25], v[24:25], v[52:53] op_sel_hi:[1,0]
	v_pk_mul_f32 v[22:23], v[22:23], v[52:53] op_sel_hi:[1,0]
	v_pk_mul_f32 v[16:17], v[16:17], v[52:53] op_sel_hi:[1,0]
	v_pk_mul_f32 v[14:15], v[14:15], v[52:53] op_sel_hi:[1,0]
	v_pk_mul_f32 v[12:13], v[12:13], v[52:53] op_sel_hi:[1,0]
	v_pk_mul_f32 v[10:11], v[10:11], v[52:53] op_sel_hi:[1,0]
	v_pk_mul_f32 v[8:9], v[8:9], v[52:53] op_sel_hi:[1,0]
	v_pk_mul_f32 v[6:7], v[6:7], v[52:53] op_sel_hi:[1,0]
	v_pk_mul_f32 v[4:5], v[4:5], v[52:53] op_sel_hi:[1,0]
	v_pk_mul_f32 v[2:3], v[2:3], v[52:53] op_sel_hi:[1,0]
	v_lshl_add_u64 v[52:53], v[42:43], 0, v[0:1]
	s_mov_b64 s[0:1], 0x400
	v_lshl_add_u64 v[42:43], v[52:53], 0, s[0:1]
	s_mov_b64 s[4:5], 0
	s_mov_b32 s95, 0x7fffffe0
	s_waitcnt vmcnt(0) lgkmcnt(0)
	v_lshlrev_b32_e32 v54, 16, v44
	v_and_b32_e32 v55, 0xffff0000, v44
	v_lshlrev_b32_e32 v44, 16, v45
	v_and_b32_e32 v45, 0xffff0000, v45
	v_lshlrev_b32_e32 v56, 16, v46
	v_and_b32_e32 v57, 0xffff0000, v46
	v_lshlrev_b32_e32 v46, 16, v47
	v_and_b32_e32 v47, 0xffff0000, v47
	v_lshlrev_b32_e32 v58, 16, v48
	v_and_b32_e32 v59, 0xffff0000, v48
	v_lshlrev_b32_e32 v48, 16, v49
	v_and_b32_e32 v49, 0xffff0000, v49
	v_lshlrev_b32_e32 v60, 16, v50
	v_and_b32_e32 v61, 0xffff0000, v50
	v_lshlrev_b32_e32 v50, 16, v51
	v_and_b32_e32 v51, 0xffff0000, v51
	v_pk_mul_f32 v[18:19], v[18:19], v[54:55]
	v_pk_mul_f32 v[20:21], v[20:21], v[44:45]
	v_pk_mul_f32 v[22:23], v[22:23], v[56:57]
	v_pk_mul_f32 v[24:25], v[24:25], v[46:47]
	v_pk_mul_f32 v[26:27], v[26:27], v[58:59]
	v_pk_mul_f32 v[28:29], v[28:29], v[48:49]
	v_pk_mul_f32 v[30:31], v[30:31], v[60:61]
	v_pk_mul_f32 v[32:33], v[32:33], v[50:51]
	v_cvt_pk_bf16_f32 v18, v18, v19
	v_cvt_pk_bf16_f32 v19, v20, v21
	v_cvt_pk_bf16_f32 v20, v22, v23
	v_cvt_pk_bf16_f32 v21, v24, v25
	v_cvt_pk_bf16_f32 v22, v26, v27
	v_cvt_pk_bf16_f32 v23, v28, v29
	v_cvt_pk_bf16_f32 v24, v30, v31
	v_cvt_pk_bf16_f32 v25, v32, v33
	global_store_dwordx2 v[52:53], v[18:19], off offset:1024
	global_store_dwordx2 v[52:53], v[20:21], off offset:1040
	global_store_dwordx2 v[52:53], v[22:23], off offset:1056
	global_store_dwordx2 v[52:53], v[24:25], off offset:1072
